# v48 + gsz division by shift (16 sites) + grid barrier: waiting workgroups poll the top-level generation word directly + gate phase LN gain/bias loads issued with the tile loads
# speedup vs baseline: 1.0032x; 1.0017x over previous
.LBB0_63:
	s_lshl_b32 s6, s78, 8
	s_add_u32 s6, s30, s6
	s_addc_u32 s7, s31, 0
	v_mov_b32_e32 v1, 0x1000
	v_mov_b32_e32 v3, 1
	global_atomic_add v3, v1, v3, s[6:7] offset:1024 sc0
	v_cvt_f32_u32_e32 v1, v2
	v_sub_u32_e32 v4, 0, v2
	v_rcp_iflag_f32_e32 v1, v1
	s_nop 0
	v_mul_f32_e32 v1, 0x4f7ffffe, v1
	v_cvt_u32_f32_e32 v1, v1
	v_mul_lo_u32 v4, v4, v1
	v_mul_hi_u32 v4, v1, v4
	v_add_u32_e32 v1, v1, v4
	s_waitcnt vmcnt(0)
	v_mul_hi_u32 v1, v3, v1
	v_mul_lo_u32 v4, v1, v2
	v_sub_u32_e32 v4, v3, v4
	v_add_u32_e32 v5, 1, v1
	v_cmp_ge_u32_e32 vcc, v4, v2
	v_add_u32_e32 v3, 1, v3
	s_nop 0
	v_cndmask_b32_e32 v1, v1, v5, vcc
	v_sub_u32_e32 v5, v4, v2
	v_cndmask_b32_e32 v4, v4, v5, vcc
	v_add_u32_e32 v5, 1, v1
	v_cmp_ge_u32_e32 vcc, v4, v2
	s_nop 1
	v_cndmask_b32_e32 v1, v1, v5, vcc
	v_mul_lo_u32 v4, v2, v1
	v_add_u32_e32 v2, v4, v2
	v_cmp_ne_u32_e32 vcc, v3, v2
	s_and_saveexec_b64 s[8:9], vcc
	s_xor_b64 s[8:9], exec, s[8:9]
	s_cbranch_execz .LBB0_76
	s_waitcnt lgkmcnt(0)
	v_mov_b32_e32 v0, 0
	s_add_u32 s12, s30, 0x3500
	s_addc_u32 s13, s31, 0
	global_load_dword v0, v0, s[12:13] sc1
	s_waitcnt vmcnt(0)
	v_cmp_eq_u32_e32 vcc, v0, v1
	s_and_saveexec_b64 s[10:11], vcc
	s_cbranch_execz .LBB0_75
	s_mov_b32 s24, 1
	s_mov_b64 s[14:15], 0
	v_mov_b32_e32 v0, 0
	s_branch .LBB0_67

.LBB0_300:
	s_mul_i32 s10, s52, 0xaaab
	s_lshr_b32 s12, s10, 17
	s_lshl_b32 s16, s12, 7
	v_add_u32_e32 v0, s16, v80
	v_mad_i64_i32 v[0:1], s[10:11], v0, s55, v[66:67]
	global_load_dwordx4 v[8:11], v[0:1], off
	global_load_dwordx4 v[12:15], v[0:1], off offset:16
	global_load_dwordx4 v[16:19], v[0:1], off offset:32
	global_load_dwordx4 v[20:23], v[0:1], off offset:48
	global_load_dwordx4 v[32:35], v[0:1], off offset:80
	global_load_dwordx4 v[36:39], v[0:1], off offset:64
	s_sub_i32 s10, s22, s12
	s_mul_i32 s17, s10, 3
	s_add_i32 s17, s17, s52
	s_add_i32 s10, s17, 24
	s_mul_hi_i32 s11, s10, 0x8200
	s_mul_i32 s10, s10, 0x8200
	s_add_u32 s10, s10, s16
	s_addc_u32 s11, s11, 0
	v_lshl_add_u64 v[0:1], s[10:11], 0, v[58:59]
	v_lshl_add_u64 v[2:3], s[10:11], 0, v[60:61]
	v_lshl_add_u64 v[4:5], s[10:11], 0, v[62:63]
	v_lshl_add_u64 v[6:7], s[10:11], 0, v[64:65]
	v_lshlrev_b64 v[0:1], 8, v[0:1]
	v_lshlrev_b64 v[2:3], 8, v[2:3]
	v_lshlrev_b64 v[4:5], 8, v[4:5]
	v_lshlrev_b64 v[6:7], 8, v[6:7]
	v_lshl_add_u64 v[0:1], v[56:57], 0, v[0:1]
	v_lshl_add_u64 v[2:3], v[56:57], 0, v[2:3]
	v_lshl_add_u64 v[4:5], v[56:57], 0, v[4:5]
	v_lshl_add_u64 v[40:41], v[56:57], 0, v[6:7]
	global_load_dwordx4 v[28:31], v[0:1], off
	global_load_dwordx4 v[24:27], v[2:3], off
	s_nop 0
	global_load_dwordx4 v[4:7], v[4:5], off
	s_nop 0
	global_load_dwordx4 v[0:3], v[40:41], off
	s_lshl_b32 s98, s17, 7
	s_ashr_i32 s99, s98, 31
	s_lshl_b64 s[98:99], s[98:99], 2
	v_lshl_add_u64 v[132:133], v[70:71], 0, s[98:99]
	v_lshl_add_u64 v[134:135], v[68:69], 0, s[98:99]
	global_load_dwordx4 v[116:119], v[132:133], off
	global_load_dwordx4 v[120:123], v[134:135], off
	global_load_dwordx4 v[124:127], v[134:135], off offset:16
	global_load_dwordx4 v[128:131], v[132:133], off offset:16
	s_waitcnt vmcnt(13)
	v_add_f32_e32 v8, 0, v8
	v_add_f32_e32 v9, 0, v9
	v_add_f32_e32 v8, v10, v8
	v_add_f32_e32 v9, v11, v9
	s_waitcnt vmcnt(12)
	v_add_f32_e32 v8, v12, v8
	v_add_f32_e32 v9, v13, v9
	v_add_f32_e32 v8, v14, v8
	v_add_f32_e32 v9, v15, v9
	s_waitcnt vmcnt(11)
	v_add_f32_e32 v8, v16, v8
	v_add_f32_e32 v9, v17, v9
	v_add_f32_e32 v8, v18, v8
	v_add_f32_e32 v9, v19, v9
	s_waitcnt vmcnt(10)
	v_add_f32_e32 v8, v20, v8
	v_add_f32_e32 v9, v21, v9
	v_add_f32_e32 v8, v22, v8
	v_add_f32_e32 v9, v23, v9
	s_waitcnt vmcnt(8)
	v_add_f32_e32 v8, v36, v8
	v_add_f32_e32 v9, v37, v9
	v_add_f32_e32 v8, v38, v8
	v_add_f32_e32 v9, v39, v9
	v_add_f32_e32 v8, v32, v8
	v_add_f32_e32 v9, v33, v9
	v_add_f32_e32 v8, v34, v8
	v_add_f32_e32 v9, v35, v9
	ds_bpermute_b32 v10, v74, v8
	ds_bpermute_b32 v11, v74, v9
	s_waitcnt lgkmcnt(1)
	v_add_f32_e32 v8, v8, v10
	s_waitcnt lgkmcnt(0)
	v_add_f32_e32 v9, v9, v11
	ds_bpermute_b32 v10, v75, v8
	ds_bpermute_b32 v11, v75, v9
	s_and_saveexec_b64 s[12:13], s[2:3]
	s_cbranch_execz .LBB0_302
	s_waitcnt lgkmcnt(1)
	v_add_f32_e32 v8, v8, v10
	v_mul_f32_e32 v8, 0x39aaaaab, v8
	s_waitcnt lgkmcnt(0)
	v_add_f32_e32 v9, v9, v11
	v_mul_f32_e32 v10, v8, v8
	v_fma_f32 v9, v9, s56, -v10
	v_max_f32_e32 v9, 0, v9
	v_add_f32_e32 v9, 0x358637bd, v9
	v_mul_f32_e32 v10, 0x4f800000, v9
	v_cmp_gt_f32_e32 vcc, s57, v9
	s_nop 1
	v_cndmask_b32_e32 v9, v9, v10, vcc
	v_sqrt_f32_e32 v10, v9
	s_nop 0
	v_add_u32_e32 v11, -1, v10
	v_fma_f32 v12, -v11, v10, v9
	v_cmp_ge_f32_e64 s[10:11], 0, v12
	v_add_u32_e32 v12, 1, v10
	s_nop 0
	v_cndmask_b32_e64 v11, v10, v11, s[10:11]
	v_fma_f32 v10, -v12, v10, v9
	v_cmp_lt_f32_e64 s[10:11], 0, v10
	s_nop 1
	v_cndmask_b32_e64 v10, v11, v12, s[10:11]
	v_mul_f32_e32 v11, 0x37800000, v10
	v_cndmask_b32_e32 v10, v10, v11, vcc
	v_cmp_class_f32_e32 vcc, v9, v84
	s_nop 1
	v_cndmask_b32_e32 v9, v10, v9, vcc
	v_div_scale_f32 v10, s[10:11], v9, v9, 1.0
	v_rcp_f32_e32 v11, v10
	s_nop 0
	v_fma_f32 v12, -v10, v11, 1.0
	v_fmac_f32_e32 v11, v12, v11
	v_div_scale_f32 v12, vcc, 1.0, v9, 1.0
	v_mul_f32_e32 v13, v12, v11
	v_fma_f32 v14, -v10, v13, v12
	v_fmac_f32_e32 v13, v14, v11
	v_fma_f32 v10, -v10, v13, v12
	v_div_fmas_f32 v10, v10, v11, v13
	v_div_fixup_f32 v9, v10, v9, 1.0
	ds_write_b64 v83, v[8:9]
.LBB0_302:
	s_or_b64 exec, exec, s[12:13]
	s_lshl_b32 s12, s17, 7
	s_ashr_i32 s13, s12, 31
	s_lshl_b64 s[14:15], s[12:13], 2
	v_lshl_add_u64 v[36:37], v[70:71], 0, s[14:15]
	s_waitcnt lgkmcnt(0)
	s_barrier
	v_lshl_add_u64 v[38:39], v[68:69], 0, s[14:15]
	s_waitcnt vmcnt(0)
	v_mov_b64_e32 v[20:21], v[116:117]
	v_mov_b64_e32 v[22:23], v[118:119]
	v_mov_b64_e32 v[12:13], v[120:121]
	v_mov_b64_e32 v[14:15], v[122:123]
	v_mov_b64_e32 v[8:9], v[124:125]
	v_mov_b64_e32 v[10:11], v[126:127]
	v_mov_b64_e32 v[16:17], v[128:129]
	v_mov_b64_e32 v[18:19], v[130:131]
	ds_read_b64 v[32:33], v85
	s_waitcnt vmcnt(7)
	v_lshlrev_b32_e32 v34, 16, v28
	v_and_b32_e32 v35, 0xffff0000, v28
	v_lshlrev_b32_e32 v28, 16, v29
	v_and_b32_e32 v29, 0xffff0000, v29
	v_lshlrev_b32_e32 v40, 16, v30
	v_and_b32_e32 v41, 0xffff0000, v30
	v_lshlrev_b32_e32 v42, 16, v31
	v_and_b32_e32 v43, 0xffff0000, v31
	v_cndmask_b32_e64 v30, 0, 1, s[8:9]
	v_cmp_ne_u32_e64 s[10:11], 1, v30
	s_waitcnt lgkmcnt(0)
	v_sub_f32_e32 v29, v29, v32
	v_sub_f32_e32 v28, v28, v32
	v_sub_f32_e32 v31, v35, v32
	v_sub_f32_e32 v30, v34, v32
	v_sub_f32_e32 v35, v43, v32
	v_sub_f32_e32 v34, v42, v32
	v_sub_f32_e32 v41, v41, v32
	v_sub_f32_e32 v40, v40, v32
	v_pk_mul_f32 v[42:43], v[30:31], v[32:33] op_sel:[0,1]
	v_pk_mul_f32 v[28:29], v[28:29], v[32:33] op_sel:[0,1]
	v_pk_mul_f32 v[40:41], v[40:41], v[32:33] op_sel:[0,1]
	v_pk_mul_f32 v[32:33], v[34:35], v[32:33] op_sel:[0,1]
	s_add_u32 s14, s50, s14
	s_addc_u32 s15, s51, s15
	s_add_i32 s33, s16, 0xffff8000
	s_andn2_b64 vcc, exec, s[8:9]
	v_lshlrev_b32_e32 v54, 2, v52
	s_waitcnt vmcnt(2)
	v_pk_fma_f32 v[30:31], v[14:15], v[28:29], v[22:23]
	v_pk_fma_f32 v[28:29], v[12:13], v[42:43], v[20:21]
	s_waitcnt vmcnt(0)
	v_pk_fma_f32 v[34:35], v[10:11], v[32:33], v[18:19]
	v_pk_fma_f32 v[32:33], v[8:9], v[40:41], v[16:17]
	v_cvt_pk_bf16_f32 v40, v28, v29
	v_cvt_pk_bf16_f32 v41, v30, v31
	v_cvt_pk_bf16_f32 v42, v32, v33
	v_cvt_pk_bf16_f32 v43, v34, v35
	ds_write_b128 v86, v[40:43] offset:36864
	s_cbranch_vccnz .LBB0_304
	v_add_u32_e32 v10, s33, v58
	v_mov_b64_e32 v[8:9], s[14:15]
	v_mad_i64_i32 v[8:9], s[8:9], v10, s58, v[8:9]
	v_lshl_add_u64 v[8:9], v[8:9], 0, v[54:55]
	global_store_dwordx4 v[8:9], v[28:31], off
	global_store_dwordx4 v[8:9], v[32:35], off offset:16
	global_load_dwordx4 v[8:11], v[38:39], off offset:16
	s_nop 0
	global_load_dwordx4 v[12:15], v[38:39], off
	global_load_dwordx4 v[16:19], v[36:37], off offset:16
	global_load_dwordx4 v[20:23], v[36:37], off

.LBB0_2844:
	s_lshl_b32 s4, s78, 8
	s_add_u32 s4, s30, s4
	s_addc_u32 s5, s31, 0
	v_mov_b32_e32 v1, 0x1000
	v_mov_b32_e32 v3, 1
	global_atomic_add v3, v1, v3, s[4:5] offset:1024 sc0
	v_cvt_f32_u32_e32 v1, v2
	v_sub_u32_e32 v4, 0, v2
	v_rcp_iflag_f32_e32 v1, v1
	s_nop 0
	v_mul_f32_e32 v1, 0x4f7ffffe, v1
	v_cvt_u32_f32_e32 v1, v1
	v_mul_lo_u32 v4, v4, v1
	v_mul_hi_u32 v4, v1, v4
	v_add_u32_e32 v1, v1, v4
	s_waitcnt vmcnt(0)
	v_mul_hi_u32 v1, v3, v1
	v_mul_lo_u32 v4, v1, v2
	v_sub_u32_e32 v4, v3, v4
	v_add_u32_e32 v5, 1, v1
	v_cmp_ge_u32_e32 vcc, v4, v2
	v_add_u32_e32 v3, 1, v3
	s_nop 0
	v_cndmask_b32_e32 v1, v1, v5, vcc
	v_sub_u32_e32 v5, v4, v2
	v_cndmask_b32_e32 v4, v4, v5, vcc
	v_add_u32_e32 v5, 1, v1
	v_cmp_ge_u32_e32 vcc, v4, v2
	s_nop 1
	v_cndmask_b32_e32 v1, v1, v5, vcc
	v_mul_lo_u32 v4, v2, v1
	v_add_u32_e32 v2, v4, v2
	v_cmp_ne_u32_e32 vcc, v3, v2
	s_and_saveexec_b64 s[8:9], vcc
	s_xor_b64 s[8:9], exec, s[8:9]
	s_cbranch_execz .LBB0_2857
	s_waitcnt lgkmcnt(0)
	v_mov_b32_e32 v0, 0
	s_add_u32 s12, s30, 0x3500
	s_addc_u32 s13, s31, 0
	global_load_dword v0, v0, s[12:13] sc1
	s_waitcnt vmcnt(0)
	v_cmp_eq_u32_e32 vcc, v0, v1
	s_and_saveexec_b64 s[10:11], vcc
	s_cbranch_execz .LBB0_2856
	s_mov_b32 s24, 1
	s_mov_b64 s[14:15], 0
	v_mov_b32_e32 v0, 0
	s_branch .LBB0_2848

.LBB0_2912:
	s_lshl_b32 s2, s78, 8
	s_add_u32 s2, s30, s2
	s_addc_u32 s3, s31, 0
	v_mov_b32_e32 v1, 0x1000
	v_mov_b32_e32 v3, 1
	global_atomic_add v3, v1, v3, s[2:3] offset:1024 sc0
	v_cvt_f32_u32_e32 v1, v2
	v_sub_u32_e32 v4, 0, v2
	v_rcp_iflag_f32_e32 v1, v1
	s_nop 0
	v_mul_f32_e32 v1, 0x4f7ffffe, v1
	v_cvt_u32_f32_e32 v1, v1
	v_mul_lo_u32 v4, v4, v1
	v_mul_hi_u32 v4, v1, v4
	v_add_u32_e32 v1, v1, v4
	s_waitcnt vmcnt(0)
	v_mul_hi_u32 v1, v3, v1
	v_mul_lo_u32 v4, v1, v2
	v_sub_u32_e32 v4, v3, v4
	v_add_u32_e32 v5, 1, v1
	v_cmp_ge_u32_e32 vcc, v4, v2
	v_add_u32_e32 v3, 1, v3
	s_nop 0
	v_cndmask_b32_e32 v1, v1, v5, vcc
	v_sub_u32_e32 v5, v4, v2
	v_cndmask_b32_e32 v4, v4, v5, vcc
	v_add_u32_e32 v5, 1, v1
	v_cmp_ge_u32_e32 vcc, v4, v2
	s_nop 1
	v_cndmask_b32_e32 v1, v1, v5, vcc
	v_mul_lo_u32 v4, v2, v1
	v_add_u32_e32 v2, v4, v2
	v_cmp_ne_u32_e32 vcc, v3, v2
	s_and_saveexec_b64 s[4:5], vcc
	s_xor_b64 s[4:5], exec, s[4:5]
	s_cbranch_execz .LBB0_2925
	s_waitcnt lgkmcnt(0)
	v_mov_b32_e32 v0, 0
	s_add_u32 s8, s30, 0x3500
	s_addc_u32 s9, s31, 0
	global_load_dword v0, v0, s[8:9] sc1
	s_waitcnt vmcnt(0)
	v_cmp_eq_u32_e32 vcc, v0, v1
	s_and_saveexec_b64 s[6:7], vcc
	s_cbranch_execz .LBB0_2924
	s_mov_b32 s20, 1
	s_mov_b64 s[10:11], 0
	v_mov_b32_e32 v0, 0
	s_branch .LBB0_2916
